# retention B1: the 12 K/V tile loads of a unit issued up front into dead registers with counted waits (were one load per vmcnt(0) round trip)
# baseline (speedup 1.0000x reference)
; __device__ __forceinline__ int v_st(int k, int c) { const int kk = (k & ~0xC) | ((k & 4) << 1) | ((k & 8) >> 1); return ((kk >> 3) * 4 + (c >> 5)) * 512 + ((kk & 7) * 32 + (c & 31)) * 2; }
; #define LAS __attribute__((address_space(3)))
; __device__ __forceinline__ unsigned pk2(float lo, float hi) { return f2bf(lo) | (f2bf(hi) << 16); }
; __device__ __forceinline__ float bflo(unsigned w) { return __uint_as_float(w << 16); }
; __device__ __forceinline__ float bfhi(unsigned w) { return __uint_as_float(w & 0xffff0000u); }
; __global__ void __launch_bounds__(NWAVES * 64, 2) mega_fwd(Args args) {
;     ...
;             for (int u = bx; u < 1024; u += G) {
;                 const int h = u & 7, gc = u >> 3;
;                 const float lgf2 = -__expf(dec_f[h]) * 1.4426950408889634f, lgb2 = -__expf(dec_b[h]) * 1.4426950408889634f;
;                 const bf16* Kp = PROJ + (size_t)gc * 128 * LDP + C_RK + h * 128;
;                 const bf16* Vp = PROJ + (size_t)gc * 128 * LDP + C_RV + h * 256;
;                 int t2 = tid; asm volatile("" : "+v"(t2));
; #pragma unroll
;                 for (int i = 0; i < 4; ++i) { const int p = t2 + 512 * i, tok = p >> 4, cb = p & 15;
;                     const v4u v = *(const v4u*)(Kp + (size_t)tok * LDP + cb * 8);
;                     const float zf = __builtin_amdgcn_exp2f(lgf2 * (float)(127 - tok)), zb = __builtin_amdgcn_exp2f(lgb2 * (float)tok);
;                     v4u of, ob;
; #pragma unroll
;                     for (int j = 0; j < 4; ++j) { const float a = bflo(v[j]), b = bfhi(v[j]); of[j] = pk2(a * zf, b * zf); ob[j] = pk2(a * zb, b * zb); }
;                     const int off = (tok >> 6) * 16384 + v_st(tok & 63, cb * 8);
;                     *(LAS v4u*)(L + off) = of; *(LAS v4u*)(L + 32768 + off) = ob; }
.LBB0_256:
	s_and_b32 s6, s0, 7
	s_lshl_b32 s5, s6, 2
	v_mov_b32_e32 v0, s5
	global_load_dword v1, v0, s[64:65]
	s_ashr_i32 s4, s0, 3
	global_load_dword v0, v0, s[66:67]
	s_mul_i32 s7, s4, 0x300000
	s_mul_hi_i32 s5, s4, 0x300000
	s_add_u32 s7, s82, s7
	v_mov_b32_e32 v8, v100
	s_addc_u32 s24, s83, s5
	s_lshl_b32 s5, s6, 7
	s_lshl_b32 s8, s6, 8
	s_add_u32 s8, s7, s8
	v_lshlrev_b32_e32 v9, 3, v8
	s_addc_u32 s9, s24, 0
	v_ashrrev_i32_e32 v27, 4, v8
	v_sub_u32_e32 v12, 0x7f, v27
	v_cvt_f32_i32_e32 v12, v12
	v_cvt_f32_i32_e32 v13, v27
	v_bfe_u32 v7, v9, 5, 2
	v_lshlrev_b32_e32 v26, 4, v8
	v_and_b32_e32 v6, 48, v26
	s_lshl_b32 s6, s6, 9
	s_add_u32 s6, s7, s6
	s_addc_u32 s7, s24, 0
	s_add_i32 s4, s5, s4
	s_ashr_i32 s5, s4, 31
	s_lshl_b64 s[4:5], s[4:5], 17
	v_lshl_add_u64 v[98:99], v[64:65], 0, s[4:5]
	v_and_b32_e32 v180, 0x78, v9
	v_lshlrev_b32_e32 v192, 1, v180
	v_lshl_add_u64 v[178:179], s[8:9], 0, v[192:193]
	v_and_b32_e32 v180, 0xf8, v9
	v_lshlrev_b32_e32 v192, 1, v180
	v_lshl_add_u64 v[182:183], s[6:7], 0, v[192:193]
	v_lshl_add_u64 v[182:183], v[182:183], 0, s[14:15]
	v_mad_i64_i32 v[184:185], s[8:9], v27, s68, v[178:179]
	global_load_dwordx4 v[130:133], v[184:185], off offset:2048
	v_add_u32_e32 v180, 0x200, v8
	v_ashrrev_i32_e32 v180, 4, v180
	v_mad_i64_i32 v[184:185], s[8:9], v180, s68, v[178:179]
	global_load_dwordx4 v[134:137], v[184:185], off offset:2048
	v_add_u32_e32 v180, 0x400, v8
	v_ashrrev_i32_e32 v180, 4, v180
	v_mad_i64_i32 v[184:185], s[8:9], v180, s68, v[178:179]
	global_load_dwordx4 v[138:141], v[184:185], off offset:2048
	v_add_u32_e32 v180, 0x600, v8
	v_ashrrev_i32_e32 v180, 4, v180
	v_mad_i64_i32 v[184:185], s[8:9], v180, s68, v[178:179]
	global_load_dwordx4 v[142:145], v[184:185], off offset:2048
	v_ashrrev_i32_e32 v180, 5, v8
	v_mad_i64_i32 v[184:185], s[8:9], v180, s68, v[182:183]
	global_load_dwordx4 v[146:149], v[184:185], off
	v_add_u32_e32 v180, 0x200, v8
	v_ashrrev_i32_e32 v180, 5, v180
	v_mad_i64_i32 v[184:185], s[8:9], v180, s68, v[182:183]
	global_load_dwordx4 v[150:153], v[184:185], off
	v_add_u32_e32 v180, 0x400, v8
	v_ashrrev_i32_e32 v180, 5, v180
	v_mad_i64_i32 v[184:185], s[8:9], v180, s68, v[182:183]
	global_load_dwordx4 v[154:157], v[184:185], off
	v_add_u32_e32 v180, 0x600, v8
	v_ashrrev_i32_e32 v180, 5, v180
	v_mad_i64_i32 v[184:185], s[8:9], v180, s68, v[182:183]
	global_load_dwordx4 v[158:161], v[184:185], off
	v_add_u32_e32 v180, 0x800, v8
	v_ashrrev_i32_e32 v180, 5, v180
	v_mad_i64_i32 v[184:185], s[8:9], v180, s68, v[182:183]
	global_load_dwordx4 v[162:165], v[184:185], off
	v_add_u32_e32 v180, 0xa00, v8
	v_ashrrev_i32_e32 v180, 5, v180
	v_mad_i64_i32 v[184:185], s[8:9], v180, s68, v[182:183]
	global_load_dwordx4 v[166:169], v[184:185], off
	v_add_u32_e32 v180, 0xc00, v8
	v_ashrrev_i32_e32 v180, 5, v180
	v_mad_i64_i32 v[184:185], s[8:9], v180, s68, v[182:183]
	global_load_dwordx4 v[170:173], v[184:185], off
	v_add_u32_e32 v180, 0xe00, v8
	v_ashrrev_i32_e32 v180, 5, v180
	v_mad_i64_i32 v[184:185], s[8:9], v180, s68, v[182:183]
	global_load_dwordx4 v[174:177], v[184:185], off
	s_waitcnt vmcnt(12)
	v_mul_f32_e32 v1, 0x3fb8aa3b, v1
	v_exp_f32_e32 v1, v1
	v_mul_f32_e32 v0, 0x3fb8aa3b, v0
	v_exp_f32_e32 v0, v0
	v_mul_f32_e32 v11, 0xbfb8aa3b, v1
	v_mul_f32_e32 v12, v11, v12
	v_mul_f32_e32 v10, 0xbfb8aa3b, v0
	v_and_b32_e32 v0, 0x78, v9
	v_lshlrev_b32_e32 v192, 1, v0
	v_lshl_add_u64 v[4:5], s[8:9], 0, v[192:193]
	v_mul_f32_e32 v13, v10, v13
	v_exp_f32_e32 v12, v12
	v_exp_f32_e32 v14, v13
	s_waitcnt vmcnt(11)
	v_mov_b64_e32 v[0:1], v[130:131]
	v_mov_b64_e32 v[2:3], v[132:133]
	v_lshlrev_b32_e32 v17, 16, v1
	v_lshlrev_b32_e32 v16, 16, v0
	v_and_b32_e32 v1, 0xffff0000, v1
	v_and_b32_e32 v0, 0xffff0000, v0
	v_lshlrev_b32_e32 v23, 16, v3
	v_lshlrev_b32_e32 v22, 16, v2
	v_and_b32_e32 v3, 0xffff0000, v3
	v_and_b32_e32 v2, 0xffff0000, v2
	v_pk_mul_f32 v[18:19], v[14:15], v[16:17] op_sel_hi:[0,1]
	v_pk_mul_f32 v[20:21], v[14:15], v[0:1] op_sel_hi:[0,1]
	v_pk_mul_f32 v[0:1], v[12:13], v[0:1] op_sel_hi:[0,1]
	v_pk_mul_f32 v[24:25], v[14:15], v[22:23] op_sel_hi:[0,1]
	v_pk_mul_f32 v[14:15], v[14:15], v[2:3] op_sel_hi:[0,1]
	v_pk_mul_f32 v[2:3], v[12:13], v[2:3] op_sel_hi:[0,1]
	v_pk_mul_f32 v[16:17], v[12:13], v[16:17] op_sel_hi:[0,1]
	v_pk_mul_f32 v[22:23], v[12:13], v[22:23] op_sel_hi:[0,1]
	v_bfe_u32 v12, v3, 16, 1
	v_bfe_u32 v13, v2, 16, 1
	v_bfe_u32 v28, v1, 16, 1
	v_add3_u32 v1, v1, v28, s33
	v_add3_u32 v2, v2, v13, s33
	v_add3_u32 v3, v3, v12, s33
	v_bfe_u32 v12, v16, 16, 1
	v_bfe_u32 v13, v17, 16, 1
	v_bfe_u32 v28, v22, 16, 1
	v_bfe_u32 v29, v0, 16, 1
	v_add3_u32 v22, v22, v28, s33
	v_add3_u32 v13, v17, v13, s33
	v_add3_u32 v12, v16, v12, s33
	v_add3_u32 v0, v0, v29, s33
	v_bfe_u32 v29, v23, 16, 1
	v_lshrrev_b32_e32 v12, 16, v12
	v_lshrrev_b32_e32 v13, 16, v13
	v_lshrrev_b32_e32 v16, 16, v22
	v_add3_u32 v23, v23, v29, s33
	v_and_or_b32 v2, v2, s54, v16
	v_and_or_b32 v1, v1, s54, v13
	v_and_or_b32 v0, v0, s54, v12
	v_bfe_u32 v12, v15, 16, 1
	v_bfe_u32 v13, v14, 16, 1
	v_bfe_u32 v16, v21, 16, 1
	v_lshrrev_b32_e32 v17, 16, v23
	v_add3_u32 v16, v21, v16, s33
	v_add3_u32 v13, v14, v13, s33
	v_add3_u32 v12, v15, v12, s33
	v_bfe_u32 v14, v18, 16, 1
	v_bfe_u32 v15, v19, 16, 1
	v_bfe_u32 v21, v25, 16, 1
	v_and_or_b32 v3, v3, s54, v17
	v_bfe_u32 v17, v20, 16, 1
	v_add3_u32 v21, v25, v21, s33
	v_add3_u32 v15, v19, v15, s33
	v_add3_u32 v14, v18, v14, s33
	v_add3_u32 v17, v20, v17, s33
	v_lshrrev_b32_e32 v18, 16, v14
	v_lshrrev_b32_e32 v19, 16, v15
	v_lshrrev_b32_e32 v15, 16, v21
	v_bfe_u32 v20, v24, 16, 1
	v_and_or_b32 v15, v12, s54, v15
	v_and_or_b32 v12, v17, s54, v18
	v_and_b32_e32 v17, 48, v27
	v_lshlrev_b32_e32 v18, 1, v27
	v_add3_u32 v20, v24, v20, s33
	v_and_or_b32 v17, v18, 8, v17
	v_lshrrev_b32_e32 v14, 16, v20
	v_lshrrev_b32_e32 v17, 1, v17
	v_and_or_b32 v14, v13, s54, v14
	v_and_or_b32 v13, v16, s54, v19
	v_lshrrev_b32_e32 v18, 1, v27
	v_or_b32_e32 v17, v17, v7
	v_and_b32_e32 v19, 3, v27
	v_lshlrev_b32_e32 v17, 9, v17
	v_and_or_b32 v18, v18, 4, v19
	v_and_b32_e32 v16, 0xffffc000, v26
	v_lshl_or_b32 v17, v18, 6, v17
	v_or3_b32 v16, v17, v16, v6
	v_add_u32_e32 v16, 0, v16
	ds_write_b128 v16, v[0:3]
	ds_write_b128 v16, v[12:15] offset:32768
	v_add_u32_e32 v12, 0x200, v8
	v_ashrrev_i32_e32 v13, 4, v12
	v_sub_u32_e32 v14, 0x7f, v13
	v_cvt_f32_i32_e32 v14, v14
	v_cvt_f32_i32_e32 v15, v13
	v_mul_f32_e32 v14, v11, v14
	v_mul_f32_e32 v15, v10, v15
	v_exp_f32_e32 v14, v14
	v_exp_f32_e32 v16, v15
	s_waitcnt vmcnt(10)
; __device__ __forceinline__ int v_st(int k, int c) { const int kk = (k & ~0xC) | ((k & 4) << 1) | ((k & 8) >> 1); return ((kk >> 3) * 4 + (c >> 5)) * 512 + ((kk & 7) * 32 + (c & 31)) * 2; }
; #define LAS __attribute__((address_space(3)))
; __device__ __forceinline__ unsigned pk2(float lo, float hi) { return f2bf(lo) | (f2bf(hi) << 16); }
; __device__ __forceinline__ float bflo(unsigned w) { return __uint_as_float(w << 16); }
; __device__ __forceinline__ float bfhi(unsigned w) { return __uint_as_float(w & 0xffff0000u); }
; __global__ void __launch_bounds__(NWAVES * 64, 2) mega_fwd(Args args) {
;     ...
;                 for (int i = 0; i < 4; ++i) { const int p = t2 + 512 * i, tok = p >> 4, cb = p & 15;
;                     const v4u v = *(const v4u*)(Kp + (size_t)tok * LDP + cb * 8);
;                     const float zf = __builtin_amdgcn_exp2f(lgf2 * (float)(127 - tok)), zb = __builtin_amdgcn_exp2f(lgb2 * (float)tok);
;                     v4u of, ob;
; #pragma unroll
;                     for (int j = 0; j < 4; ++j) { const float a = bflo(v[j]), b = bfhi(v[j]); of[j] = pk2(a * zf, b * zf); ob[j] = pk2(a * zb, b * zb); }
;                     const int off = (tok >> 6) * 16384 + v_st(tok & 63, cb * 8);
;                     *(LAS v4u*)(L + off) = of; *(LAS v4u*)(L + 32768 + off) = ob; }
	v_mov_b64_e32 v[0:1], v[134:135]
	v_mov_b64_e32 v[2:3], v[136:137]
	v_lshlrev_b32_e32 v19, 16, v1
	v_lshlrev_b32_e32 v18, 16, v0
	v_and_b32_e32 v1, 0xffff0000, v1
	v_and_b32_e32 v0, 0xffff0000, v0
	v_lshlrev_b32_e32 v25, 16, v3
	v_lshlrev_b32_e32 v24, 16, v2
	v_and_b32_e32 v3, 0xffff0000, v3
	v_and_b32_e32 v2, 0xffff0000, v2
	v_pk_mul_f32 v[20:21], v[16:17], v[18:19] op_sel_hi:[0,1]
	v_pk_mul_f32 v[22:23], v[16:17], v[0:1] op_sel_hi:[0,1]
	v_pk_mul_f32 v[0:1], v[14:15], v[0:1] op_sel_hi:[0,1]
	v_pk_mul_f32 v[26:27], v[16:17], v[24:25] op_sel_hi:[0,1]
	v_pk_mul_f32 v[16:17], v[16:17], v[2:3] op_sel_hi:[0,1]
	v_pk_mul_f32 v[2:3], v[14:15], v[2:3] op_sel_hi:[0,1]
	v_pk_mul_f32 v[18:19], v[14:15], v[18:19] op_sel_hi:[0,1]
	v_pk_mul_f32 v[24:25], v[14:15], v[24:25] op_sel_hi:[0,1]
	v_bfe_u32 v14, v3, 16, 1
	v_bfe_u32 v15, v2, 16, 1
	v_bfe_u32 v28, v1, 16, 1
	v_add3_u32 v1, v1, v28, s33
	v_add3_u32 v2, v2, v15, s33
	v_add3_u32 v3, v3, v14, s33
	v_bfe_u32 v14, v18, 16, 1
	v_bfe_u32 v15, v19, 16, 1
	v_bfe_u32 v28, v24, 16, 1
	v_bfe_u32 v29, v0, 16, 1
	v_add3_u32 v24, v24, v28, s33
	v_add3_u32 v15, v19, v15, s33
	v_add3_u32 v14, v18, v14, s33
	v_add3_u32 v0, v0, v29, s33
	v_bfe_u32 v29, v25, 16, 1
	v_lshrrev_b32_e32 v14, 16, v14
	v_lshrrev_b32_e32 v15, 16, v15
	v_lshrrev_b32_e32 v18, 16, v24
	v_add3_u32 v25, v25, v29, s33
	v_and_or_b32 v2, v2, s54, v18
	v_and_or_b32 v1, v1, s54, v15
	v_and_or_b32 v0, v0, s54, v14
	v_bfe_u32 v14, v17, 16, 1
	v_bfe_u32 v15, v16, 16, 1
	v_bfe_u32 v18, v23, 16, 1
	v_lshrrev_b32_e32 v19, 16, v25
	v_add3_u32 v18, v23, v18, s33
	v_add3_u32 v15, v16, v15, s33
	v_add3_u32 v14, v17, v14, s33
	v_bfe_u32 v16, v20, 16, 1
	v_bfe_u32 v17, v21, 16, 1
	v_bfe_u32 v23, v27, 16, 1
	v_and_or_b32 v3, v3, s54, v19
	v_bfe_u32 v19, v22, 16, 1
	v_add3_u32 v23, v27, v23, s33
	v_add3_u32 v17, v21, v17, s33
	v_add3_u32 v16, v20, v16, s33
	v_add3_u32 v19, v22, v19, s33
	v_lshrrev_b32_e32 v20, 16, v16
	v_lshrrev_b32_e32 v21, 16, v17
	v_lshrrev_b32_e32 v17, 16, v23
	v_and_or_b32 v17, v14, s54, v17
	v_and_or_b32 v14, v19, s54, v20
	v_and_b32_e32 v19, 48, v13
	v_lshlrev_b32_e32 v20, 1, v13
	v_bfe_u32 v22, v26, 16, 1
	v_and_or_b32 v19, v20, 8, v19
	v_add3_u32 v22, v26, v22, s33
	v_lshrrev_b32_e32 v19, 1, v19
	v_lshrrev_b32_e32 v16, 16, v22
	v_lshrrev_b32_e32 v20, 1, v13
	v_or_b32_e32 v19, v19, v7
	v_and_b32_e32 v13, 3, v13
	v_and_or_b32 v16, v15, s54, v16
	v_and_or_b32 v15, v18, s54, v21
	v_lshlrev_b32_e32 v18, 4, v12
	v_lshlrev_b32_e32 v19, 9, v19
	v_and_or_b32 v13, v20, 4, v13
	v_and_b32_e32 v18, 0xffffc000, v18
	v_lshl_or_b32 v13, v13, 6, v19
	v_or3_b32 v13, v13, v18, v6
	v_add_u32_e32 v13, 0, v13
	ds_write_b128 v13, v[0:3]
	ds_write_b128 v13, v[14:17] offset:32768
	v_add_u32_e32 v13, 0x400, v8
	v_ashrrev_i32_e32 v28, 4, v13
	v_sub_u32_e32 v14, 0x7f, v28
	v_cvt_f32_i32_e32 v14, v14
	v_cvt_f32_i32_e32 v15, v28
	v_mul_f32_e32 v14, v11, v14
	v_mul_f32_e32 v15, v10, v15
	v_exp_f32_e32 v14, v14
	v_exp_f32_e32 v16, v15
	s_waitcnt vmcnt(9)
	v_mov_b64_e32 v[0:1], v[138:139]
	v_mov_b64_e32 v[2:3], v[140:141]
	v_lshlrev_b32_e32 v19, 16, v1
	v_lshlrev_b32_e32 v18, 16, v0
	v_and_b32_e32 v1, 0xffff0000, v1
	v_and_b32_e32 v0, 0xffff0000, v0
	v_lshlrev_b32_e32 v25, 16, v3
	v_lshlrev_b32_e32 v24, 16, v2
	v_and_b32_e32 v3, 0xffff0000, v3
	v_and_b32_e32 v2, 0xffff0000, v2
	v_pk_mul_f32 v[20:21], v[16:17], v[18:19] op_sel_hi:[0,1]
	v_pk_mul_f32 v[22:23], v[16:17], v[0:1] op_sel_hi:[0,1]
	v_pk_mul_f32 v[0:1], v[14:15], v[0:1] op_sel_hi:[0,1]
	v_pk_mul_f32 v[26:27], v[16:17], v[24:25] op_sel_hi:[0,1]
	v_pk_mul_f32 v[16:17], v[16:17], v[2:3] op_sel_hi:[0,1]
	v_pk_mul_f32 v[2:3], v[14:15], v[2:3] op_sel_hi:[0,1]
	v_pk_mul_f32 v[18:19], v[14:15], v[18:19] op_sel_hi:[0,1]
	v_pk_mul_f32 v[24:25], v[14:15], v[24:25] op_sel_hi:[0,1]
	v_bfe_u32 v14, v3, 16, 1
	v_bfe_u32 v15, v2, 16, 1
	v_bfe_u32 v29, v1, 16, 1
	v_add3_u32 v1, v1, v29, s33
	v_add3_u32 v2, v2, v15, s33
	v_add3_u32 v3, v3, v14, s33
	v_bfe_u32 v14, v18, 16, 1
	v_bfe_u32 v15, v19, 16, 1
	v_bfe_u32 v29, v24, 16, 1
	v_bfe_u32 v30, v0, 16, 1
	v_add3_u32 v24, v24, v29, s33
	v_add3_u32 v15, v19, v15, s33
	v_add3_u32 v14, v18, v14, s33
	v_add3_u32 v0, v0, v30, s33
	v_bfe_u32 v30, v25, 16, 1
	v_lshrrev_b32_e32 v14, 16, v14
	v_lshrrev_b32_e32 v15, 16, v15
	v_lshrrev_b32_e32 v18, 16, v24
	v_add3_u32 v25, v25, v30, s33
	v_and_or_b32 v2, v2, s54, v18
	v_and_or_b32 v1, v1, s54, v15
	v_and_or_b32 v0, v0, s54, v14
	v_bfe_u32 v14, v17, 16, 1
	v_bfe_u32 v15, v16, 16, 1
	v_bfe_u32 v18, v23, 16, 1
	v_lshrrev_b32_e32 v19, 16, v25
	v_add3_u32 v18, v23, v18, s33
	v_add3_u32 v15, v16, v15, s33
	v_add3_u32 v14, v17, v14, s33
	v_bfe_u32 v16, v20, 16, 1
	v_bfe_u32 v17, v21, 16, 1
	v_bfe_u32 v23, v27, 16, 1
	v_and_or_b32 v3, v3, s54, v19
	v_bfe_u32 v19, v22, 16, 1
	v_add3_u32 v23, v27, v23, s33
	v_add3_u32 v17, v21, v17, s33
	v_add3_u32 v16, v20, v16, s33
	v_add3_u32 v19, v22, v19, s33
	v_lshrrev_b32_e32 v20, 16, v16
	v_lshrrev_b32_e32 v21, 16, v17
	v_lshrrev_b32_e32 v17, 16, v23
	v_bfe_u32 v22, v26, 16, 1
	v_and_or_b32 v17, v14, s54, v17
	v_and_or_b32 v14, v19, s54, v20
	v_and_b32_e32 v19, 48, v28
	v_lshlrev_b32_e32 v20, 1, v28
	v_add3_u32 v22, v26, v22, s33
	v_and_or_b32 v19, v20, 8, v19
	v_lshrrev_b32_e32 v16, 16, v22
	v_lshrrev_b32_e32 v19, 1, v19
	v_and_or_b32 v16, v15, s54, v16
	v_and_or_b32 v15, v18, s54, v21
	v_lshrrev_b32_e32 v20, 1, v28
	v_or_b32_e32 v19, v19, v7
	v_and_b32_e32 v21, 3, v28
	v_lshlrev_b32_e32 v18, 4, v13
	v_lshlrev_b32_e32 v19, 9, v19
	v_and_or_b32 v20, v20, 4, v21
	v_and_b32_e32 v18, 0xffffc000, v18
	v_lshl_or_b32 v19, v20, 6, v19
	v_or3_b32 v18, v19, v18, v6
	v_add_u32_e32 v18, 0, v18
	ds_write_b128 v18, v[0:3]
	ds_write_b128 v18, v[14:17] offset:32768
	v_add_u32_e32 v14, 0x600, v8
	v_ashrrev_i32_e32 v15, 4, v14
	v_sub_u32_e32 v4, 0x7f, v15
	v_cvt_f32_i32_e32 v4, v4
	v_cvt_f32_i32_e32 v5, v15
	v_mul_f32_e32 v4, v11, v4
	v_mul_f32_e32 v5, v10, v5
	v_exp_f32_e32 v4, v4
	v_exp_f32_e32 v10, v5
	s_waitcnt vmcnt(8)
; __device__ __forceinline__ int v_st(int k, int c) { const int kk = (k & ~0xC) | ((k & 4) << 1) | ((k & 8) >> 1); return ((kk >> 3) * 4 + (c >> 5)) * 512 + ((kk & 7) * 32 + (c & 31)) * 2; }
; #define LAS __attribute__((address_space(3)))
; __device__ __forceinline__ unsigned pk2(float lo, float hi) { return f2bf(lo) | (f2bf(hi) << 16); }
; __device__ __forceinline__ float bflo(unsigned w) { return __uint_as_float(w << 16); }
; __device__ __forceinline__ float bfhi(unsigned w) { return __uint_as_float(w & 0xffff0000u); }
; __global__ void __launch_bounds__(NWAVES * 64, 2) mega_fwd(Args args) {
;     ...
;                 for (int i = 0; i < 4; ++i) { const int p = t2 + 512 * i, tok = p >> 4, cb = p & 15;
;                     const v4u v = *(const v4u*)(Kp + (size_t)tok * LDP + cb * 8);
;                     const float zf = __builtin_amdgcn_exp2f(lgf2 * (float)(127 - tok)), zb = __builtin_amdgcn_exp2f(lgb2 * (float)tok);
;                     v4u of, ob;
; #pragma unroll
;                     for (int j = 0; j < 4; ++j) { const float a = bflo(v[j]), b = bfhi(v[j]); of[j] = pk2(a * zf, b * zf); ob[j] = pk2(a * zb, b * zb); }
;                     const int off = (tok >> 6) * 16384 + v_st(tok & 63, cb * 8);
;                     *(LAS v4u*)(L + off) = of; *(LAS v4u*)(L + 32768 + off) = ob; }
; #pragma unroll
;                 for (int i = 0; i < 8; ++i) { const int p = t2 + 512 * i, tok = p >> 5, col = (p & 31) * 8;
;                     const v4u v = *(const v4u*)(Vp + (size_t)tok * LDP + col);
;                     *(LAS v4u*)(L + 65536 + ((tok >> 6) * 2 + (col >> 7)) * 16384 + v_st(tok & 63, col & 127)) = v; }
	v_mov_b64_e32 v[0:1], v[142:143]
	v_mov_b64_e32 v[2:3], v[144:145]
	v_lshlrev_b32_e32 v17, 16, v1
	v_lshlrev_b32_e32 v16, 16, v0
	v_and_b32_e32 v1, 0xffff0000, v1
	v_and_b32_e32 v0, 0xffff0000, v0
	v_lshlrev_b32_e32 v23, 16, v3
	v_lshlrev_b32_e32 v22, 16, v2
	v_and_b32_e32 v3, 0xffff0000, v3
	v_and_b32_e32 v2, 0xffff0000, v2
	v_pk_mul_f32 v[18:19], v[10:11], v[16:17] op_sel_hi:[0,1]
	v_pk_mul_f32 v[20:21], v[10:11], v[0:1] op_sel_hi:[0,1]
	v_pk_mul_f32 v[0:1], v[4:5], v[0:1] op_sel_hi:[0,1]
	v_pk_mul_f32 v[24:25], v[10:11], v[22:23] op_sel_hi:[0,1]
	v_pk_mul_f32 v[10:11], v[10:11], v[2:3] op_sel_hi:[0,1]
	v_pk_mul_f32 v[2:3], v[4:5], v[2:3] op_sel_hi:[0,1]
	v_pk_mul_f32 v[16:17], v[4:5], v[16:17] op_sel_hi:[0,1]
	v_pk_mul_f32 v[22:23], v[4:5], v[22:23] op_sel_hi:[0,1]
	v_bfe_u32 v4, v3, 16, 1
	v_bfe_u32 v5, v2, 16, 1
	v_bfe_u32 v26, v1, 16, 1
	v_bfe_u32 v27, v0, 16, 1
	v_add3_u32 v0, v0, v27, s33
	v_add3_u32 v1, v1, v26, s33
	v_add3_u32 v2, v2, v5, s33
	v_add3_u32 v3, v3, v4, s33
	v_bfe_u32 v4, v16, 16, 1
	v_bfe_u32 v5, v17, 16, 1
	v_bfe_u32 v26, v22, 16, 1
	v_bfe_u32 v27, v23, 16, 1
	v_add3_u32 v23, v23, v27, s33
	v_add3_u32 v22, v22, v26, s33
	v_add3_u32 v5, v17, v5, s33
	v_add3_u32 v4, v16, v4, s33
	v_lshrrev_b32_e32 v4, 16, v4
	v_lshrrev_b32_e32 v5, 16, v5
	v_lshrrev_b32_e32 v16, 16, v22
	v_lshrrev_b32_e32 v17, 16, v23
	v_and_or_b32 v3, v3, s54, v17
	v_and_or_b32 v2, v2, s54, v16
	v_and_or_b32 v1, v1, s54, v5
	v_and_or_b32 v0, v0, s54, v4
	v_bfe_u32 v4, v11, 16, 1
	v_bfe_u32 v5, v10, 16, 1
	v_bfe_u32 v16, v21, 16, 1
	v_bfe_u32 v17, v20, 16, 1
	v_add3_u32 v20, v20, v17, s33
	v_add3_u32 v16, v21, v16, s33
	v_add3_u32 v5, v10, v5, s33
	v_add3_u32 v4, v11, v4, s33
	v_bfe_u32 v10, v18, 16, 1
	v_bfe_u32 v11, v19, 16, 1
	v_bfe_u32 v17, v24, 16, 1
	v_bfe_u32 v21, v25, 16, 1
	v_add3_u32 v21, v25, v21, s33
	v_add3_u32 v17, v24, v17, s33
	v_add3_u32 v11, v19, v11, s33
	v_add3_u32 v10, v18, v10, s33
	v_lshrrev_b32_e32 v10, 16, v10
	v_lshrrev_b32_e32 v11, 16, v11
	v_lshrrev_b32_e32 v17, 16, v17
	v_lshrrev_b32_e32 v18, 16, v21
	v_and_or_b32 v19, v4, s54, v18
	v_and_or_b32 v18, v5, s54, v17
	v_and_or_b32 v17, v16, s54, v11
	v_and_or_b32 v16, v20, s54, v10
	v_and_b32_e32 v5, 48, v15
	v_lshlrev_b32_e32 v10, 1, v15
	v_and_or_b32 v5, v10, 8, v5
	v_lshrrev_b32_e32 v5, 1, v5
	v_lshrrev_b32_e32 v10, 1, v15
	v_or_b32_e32 v5, v5, v7
	v_and_b32_e32 v11, 3, v15
	v_lshlrev_b32_e32 v4, 4, v14
	v_lshlrev_b32_e32 v5, 9, v5
	v_and_or_b32 v10, v10, 4, v11
	v_and_b32_e32 v4, 0xffffc000, v4
	v_lshl_or_b32 v5, v10, 6, v5
	v_or3_b32 v4, v5, v4, v6
	v_add_u32_e32 v4, 0, v4
	ds_write_b128 v4, v[0:3]
	ds_write_b128 v4, v[16:19] offset:32768
	v_and_b32_e32 v0, 0xf8, v9
	v_lshlrev_b32_e32 v192, 1, v0
	v_lshl_add_u64 v[0:1], s[6:7], 0, v[192:193]
	v_lshl_add_u64 v[0:1], v[0:1], 0, s[14:15]
	v_ashrrev_i32_e32 v5, 5, v8
	v_bfe_u32 v4, v9, 7, 1
	v_and_b32_e32 v3, 48, v5
	v_lshlrev_b32_e32 v9, 1, v5
	v_and_or_b32 v3, v9, 8, v3
	v_lshrrev_b32_e32 v2, 10, v8
	v_lshrrev_b32_e32 v3, 1, v3
	v_and_or_b32 v2, v2, s69, v4
	v_lshrrev_b32_e32 v9, 1, v5
	v_or_b32_e32 v3, v3, v7
	v_and_b32_e32 v5, 3, v5
	v_lshlrev_b32_e32 v2, 14, v2
	s_add_i32 s6, 0, 0x10000
	v_lshlrev_b32_e32 v3, 9, v3
	v_and_or_b32 v5, v9, 4, v5
	v_lshlrev_b32_e32 v5, 6, v5
	v_add3_u32 v2, s6, v2, v3
	v_add3_u32 v2, v2, v5, v6
	v_ashrrev_i32_e32 v5, 5, v12
	v_lshlrev_b32_e32 v9, 1, v5
	s_waitcnt vmcnt(7)
	ds_write_b128 v2, v[146:149]
	v_and_b32_e32 v3, 48, v5
	v_and_or_b32 v3, v9, 8, v3
	v_lshrrev_b32_e32 v2, 10, v12
	v_lshrrev_b32_e32 v3, 1, v3
	v_and_or_b32 v2, v2, s69, v4
	v_lshrrev_b32_e32 v9, 1, v5
	v_or_b32_e32 v3, v3, v7
	v_and_b32_e32 v5, 3, v5
	v_lshlrev_b32_e32 v2, 14, v2
	v_lshlrev_b32_e32 v3, 9, v3
	v_and_or_b32 v5, v9, 4, v5
	v_lshlrev_b32_e32 v5, 6, v5
	v_add3_u32 v2, s6, v2, v3
	v_add3_u32 v2, v2, v5, v6
	v_ashrrev_i32_e32 v5, 5, v13
	v_lshlrev_b32_e32 v9, 1, v5
	s_waitcnt vmcnt(6)
	ds_write_b128 v2, v[150:153]
	v_and_b32_e32 v3, 48, v5
	v_and_or_b32 v3, v9, 8, v3
	v_lshrrev_b32_e32 v2, 10, v13
	v_lshrrev_b32_e32 v3, 1, v3
	v_and_or_b32 v2, v2, s69, v4
	v_lshrrev_b32_e32 v9, 1, v5
	v_or_b32_e32 v3, v3, v7
	v_and_b32_e32 v5, 3, v5
	v_lshlrev_b32_e32 v2, 14, v2
	v_lshlrev_b32_e32 v3, 9, v3
	v_and_or_b32 v5, v9, 4, v5
	v_lshlrev_b32_e32 v5, 6, v5
	v_add3_u32 v2, s6, v2, v3
	v_add3_u32 v2, v2, v5, v6
	v_ashrrev_i32_e32 v5, 5, v14
	v_lshlrev_b32_e32 v9, 1, v5
	s_waitcnt vmcnt(5)
	ds_write_b128 v2, v[154:157]
	v_and_b32_e32 v3, 48, v5
	v_and_or_b32 v3, v9, 8, v3
	v_lshrrev_b32_e32 v2, 10, v14
	v_lshrrev_b32_e32 v3, 1, v3
	v_and_or_b32 v2, v2, s69, v4
	v_lshrrev_b32_e32 v9, 1, v5
	v_or_b32_e32 v3, v3, v7
	v_and_b32_e32 v5, 3, v5
	v_lshlrev_b32_e32 v2, 14, v2
	v_lshlrev_b32_e32 v3, 9, v3
	v_and_or_b32 v5, v9, 4, v5
	v_lshlrev_b32_e32 v5, 6, v5
	v_add3_u32 v2, s6, v2, v3
	v_add3_u32 v2, v2, v5, v6
	v_add_u32_e32 v5, 0x800, v8
	v_ashrrev_i32_e32 v9, 5, v5
	s_waitcnt vmcnt(4)
	ds_write_b128 v2, v[158:161]
	v_lshrrev_b32_e32 v2, 10, v5
	v_and_b32_e32 v3, 48, v9
	v_lshlrev_b32_e32 v5, 1, v9
	v_and_or_b32 v3, v5, 8, v3
	v_lshrrev_b32_e32 v3, 1, v3
	v_and_or_b32 v2, v2, s69, v4
	v_lshrrev_b32_e32 v5, 1, v9
	v_or_b32_e32 v3, v3, v7
	v_and_b32_e32 v9, 3, v9
	v_lshlrev_b32_e32 v2, 14, v2
	v_lshlrev_b32_e32 v3, 9, v3
	v_and_or_b32 v5, v5, 4, v9
	v_lshlrev_b32_e32 v5, 6, v5
	v_add3_u32 v2, s6, v2, v3
	v_add3_u32 v2, v2, v5, v6
	v_add_u32_e32 v5, 0xa00, v8
	v_ashrrev_i32_e32 v9, 5, v5
	s_waitcnt vmcnt(3)
	ds_write_b128 v2, v[162:165]
	v_lshrrev_b32_e32 v2, 10, v5
	v_and_b32_e32 v3, 48, v9
	v_lshlrev_b32_e32 v5, 1, v9
	v_and_or_b32 v3, v5, 8, v3
	v_lshrrev_b32_e32 v3, 1, v3
	v_and_or_b32 v2, v2, s69, v4
	v_lshrrev_b32_e32 v5, 1, v9
	v_or_b32_e32 v3, v3, v7
	v_and_b32_e32 v9, 3, v9
	v_lshlrev_b32_e32 v2, 14, v2
	v_lshlrev_b32_e32 v3, 9, v3
	v_and_or_b32 v5, v5, 4, v9
	v_lshlrev_b32_e32 v5, 6, v5
	v_add3_u32 v2, s6, v2, v3
	v_add3_u32 v2, v2, v5, v6
	v_add_u32_e32 v5, 0xc00, v8
	v_ashrrev_i32_e32 v9, 5, v5
	s_waitcnt vmcnt(2)
	ds_write_b128 v2, v[166:169]
	v_lshrrev_b32_e32 v2, 10, v5
	v_and_b32_e32 v3, 48, v9
	v_lshlrev_b32_e32 v5, 1, v9
	v_and_or_b32 v3, v5, 8, v3
	v_lshrrev_b32_e32 v3, 1, v3
	v_and_or_b32 v2, v2, s69, v4
	v_lshrrev_b32_e32 v5, 1, v9
	v_or_b32_e32 v3, v3, v7
	v_and_b32_e32 v9, 3, v9
	v_lshlrev_b32_e32 v2, 14, v2
	v_lshlrev_b32_e32 v3, 9, v3
	v_and_or_b32 v5, v5, 4, v9
	v_lshlrev_b32_e32 v5, 6, v5
	v_add3_u32 v2, s6, v2, v3
	v_add3_u32 v2, v2, v5, v6
	v_add_u32_e32 v5, 0xe00, v8
	v_ashrrev_i32_e32 v8, 5, v5
	v_lshrrev_b32_e32 v5, 10, v5
	v_and_or_b32 v4, v5, s69, v4
	v_and_b32_e32 v5, 48, v8
	v_lshlrev_b32_e32 v9, 1, v8
	v_and_or_b32 v5, v9, 8, v5
	v_lshrrev_b32_e32 v5, 1, v5
	v_lshrrev_b32_e32 v9, 1, v8
	v_or_b32_e32 v5, v5, v7
	v_and_b32_e32 v7, 3, v8
	v_lshlrev_b32_e32 v4, 14, v4
	v_lshlrev_b32_e32 v5, 9, v5
	v_and_or_b32 v7, v9, 4, v7
	v_lshlrev_b32_e32 v7, 6, v7
	v_add3_u32 v4, s6, v4, v5
	v_add3_u32 v4, v4, v7, v6
	s_waitcnt vmcnt(1)
	ds_write_b128 v2, v[170:173]
	s_waitcnt vmcnt(0)
	ds_write_b128 v4, v[174:177]
	s_waitcnt lgkmcnt(0)
	s_barrier
; __device__ __forceinline__ int v_rd_base(int lane) { return ((lane & 3) << 3) | (((lane >> 2) & 3) << 6) | (((lane >> 4) & 1) << 5) | (((lane >> 5) & 1) << 8); }
; __global__ void __launch_bounds__(NWAVES * 64, 2) mega_fwd(Args args) {
;     ...
;                 const int abase = v_rd_base(lane) + rb * 512, bbase = 65536 + v_rd_base(lane) + half * 16384;
; #pragma unroll
;                 for (int dir = 0; dir < 2; ++dir) {
;                     f32x16 acc[4] = {};
; #pragma unroll
;                     for (int tt = 0; tt < 2; ++tt) {
;                         const int ab = abase + dir * 32768 + tt * 16384, bb = bbase + tt * 32768;
;     ...
;                         B1_STEP(0); B1_STEP(1); B1_STEP(2); B1_STEP(3);
	ds_read_b64_tr_b16 v[0:1], v102 offset:0
	ds_read_b64_tr_b16 v[2:3], v102 offset:0x800
	ds_read_b64_tr_b16 v[4:5], v101 offset:0
	ds_read_b64_tr_b16 v[6:7], v101 offset:0x800
	ds_read_b64_tr_b16 v[8:9], v101 offset:0x200
	ds_read_b64_tr_b16 v[10:11], v101 offset:0xa00
	ds_read_b64_tr_b16 v[12:13], v101 offset:0x400
	ds_read_b64_tr_b16 v[14:15], v101 offset:0xc00
	ds_read_b64_tr_b16 v[108:109], v101 offset:0x600
	ds_read_b64_tr_b16 v[110:111], v101 offset:0xe00
	s_waitcnt lgkmcnt(0)
	s_nop 0
	v_mfma_f32_32x32x16_bf16 v[16:31], v[0:3], v[4:7], 0
	v_mfma_f32_32x32x16_bf16 v[48:63], v[0:3], v[8:11], 0
	v_mfma_f32_32x32x16_bf16 v[32:47], v[0:3], v[12:15], 0
	v_mfma_f32_32x32x16_bf16 v[0:15], v[0:3], v[108:111], 0
	ds_read_b64_tr_b16 v[108:109], v102 offset:0x1000
	ds_read_b64_tr_b16 v[110:111], v102 offset:0x1800
	ds_read_b64_tr_b16 v[112:113], v101 offset:0x1000
	ds_read_b64_tr_b16 v[114:115], v101 offset:0x1800
	ds_read_b64_tr_b16 v[116:117], v101 offset:0x1200
	ds_read_b64_tr_b16 v[118:119], v101 offset:0x1a00
	ds_read_b64_tr_b16 v[120:121], v101 offset:0x1400
	ds_read_b64_tr_b16 v[122:123], v101 offset:0x1c00
	ds_read_b64_tr_b16 v[124:125], v101 offset:0x1600
	ds_read_b64_tr_b16 v[126:127], v101 offset:0x1e00
	s_waitcnt lgkmcnt(0)
	s_nop 0
	v_mfma_f32_32x32x16_bf16 v[16:31], v[108:111], v[112:115], v[16:31]
	v_mfma_f32_32x32x16_bf16 v[48:63], v[108:111], v[116:119], v[48:63]
	v_mfma_f32_32x32x16_bf16 v[32:47], v[108:111], v[120:123], v[32:47]
	v_mfma_f32_32x32x16_bf16 v[0:15], v[108:111], v[124:127], v[0:15]
	ds_read_b64_tr_b16 v[108:109], v102 offset:0x2000
	ds_read_b64_tr_b16 v[110:111], v102 offset:0x2800
	ds_read_b64_tr_b16 v[112:113], v101 offset:0x2000
	ds_read_b64_tr_b16 v[114:115], v101 offset:0x2800
	ds_read_b64_tr_b16 v[116:117], v101 offset:0x2200
	ds_read_b64_tr_b16 v[118:119], v101 offset:0x2a00
	ds_read_b64_tr_b16 v[120:121], v101 offset:0x2400
	ds_read_b64_tr_b16 v[122:123], v101 offset:0x2c00
	ds_read_b64_tr_b16 v[124:125], v101 offset:0x2600
	ds_read_b64_tr_b16 v[126:127], v101 offset:0x2e00
	s_waitcnt lgkmcnt(0)
	s_nop 0
	v_mfma_f32_32x32x16_bf16 v[16:31], v[108:111], v[112:115], v[16:31]
	v_mfma_f32_32x32x16_bf16 v[48:63], v[108:111], v[116:119], v[48:63]
	v_mfma_f32_32x32x16_bf16 v[32:47], v[108:111], v[120:123], v[32:47]
	v_mfma_f32_32x32x16_bf16 v[0:15], v[108:111], v[124:127], v[0:15]
	ds_read_b64_tr_b16 v[108:109], v102 offset:0x3000
	ds_read_b64_tr_b16 v[110:111], v102 offset:0x3800
	ds_read_b64_tr_b16 v[112:113], v101 offset:0x3000
	ds_read_b64_tr_b16 v[114:115], v101 offset:0x3800
	ds_read_b64_tr_b16 v[116:117], v101 offset:0x3200
	ds_read_b64_tr_b16 v[118:119], v101 offset:0x3a00
	ds_read_b64_tr_b16 v[120:121], v101 offset:0x3400
	ds_read_b64_tr_b16 v[122:123], v101 offset:0x3c00
	ds_read_b64_tr_b16 v[124:125], v101 offset:0x3600
	ds_read_b64_tr_b16 v[126:127], v101 offset:0x3e00
	s_waitcnt lgkmcnt(0)
	s_nop 0
	v_mfma_f32_32x32x16_bf16 v[16:31], v[108:111], v[112:115], v[16:31]
	v_mfma_f32_32x32x16_bf16 v[48:63], v[108:111], v[116:119], v[48:63]
	v_mfma_f32_32x32x16_bf16 v[32:47], v[108:111], v[120:123], v[32:47]
	v_mfma_f32_32x32x16_bf16 v[0:15], v[108:111], v[124:127], v[0:15]
	ds_read_b64_tr_b16 v[108:109], v103 offset:0
	ds_read_b64_tr_b16 v[110:111], v103 offset:0x800
	ds_read_b64_tr_b16 v[112:113], v104 offset:0
	ds_read_b64_tr_b16 v[114:115], v104 offset:0x800
	ds_read_b64_tr_b16 v[116:117], v104 offset:0x200
	ds_read_b64_tr_b16 v[118:119], v104 offset:0xa00
	ds_read_b64_tr_b16 v[120:121], v104 offset:0x400
	ds_read_b64_tr_b16 v[122:123], v104 offset:0xc00
	ds_read_b64_tr_b16 v[124:125], v104 offset:0x600
	ds_read_b64_tr_b16 v[126:127], v104 offset:0xe00
	s_waitcnt lgkmcnt(0)
	s_nop 0
	v_mfma_f32_32x32x16_bf16 v[16:31], v[108:111], v[112:115], v[16:31]
	v_mfma_f32_32x32x16_bf16 v[48:63], v[108:111], v[116:119], v[48:63]
	v_mfma_f32_32x32x16_bf16 v[32:47], v[108:111], v[120:123], v[32:47]
	v_mfma_f32_32x32x16_bf16 v[0:15], v[108:111], v[124:127], v[0:15]
	ds_read_b64_tr_b16 v[108:109], v103 offset:0x1000
	ds_read_b64_tr_b16 v[110:111], v103 offset:0x1800
	ds_read_b64_tr_b16 v[112:113], v104 offset:0x1000
	ds_read_b64_tr_b16 v[114:115], v104 offset:0x1800
	ds_read_b64_tr_b16 v[116:117], v104 offset:0x1200
	ds_read_b64_tr_b16 v[118:119], v104 offset:0x1a00
	ds_read_b64_tr_b16 v[120:121], v104 offset:0x1400
	ds_read_b64_tr_b16 v[122:123], v104 offset:0x1c00
	ds_read_b64_tr_b16 v[124:125], v104 offset:0x1600
	ds_read_b64_tr_b16 v[126:127], v104 offset:0x1e00
	s_waitcnt lgkmcnt(0)
	s_nop 0
	v_mfma_f32_32x32x16_bf16 v[16:31], v[108:111], v[112:115], v[16:31]
	v_mfma_f32_32x32x16_bf16 v[48:63], v[108:111], v[116:119], v[48:63]
	v_mfma_f32_32x32x16_bf16 v[32:47], v[108:111], v[120:123], v[32:47]
	v_mfma_f32_32x32x16_bf16 v[0:15], v[108:111], v[124:127], v[0:15]
	ds_read_b64_tr_b16 v[108:109], v103 offset:0x2000
	ds_read_b64_tr_b16 v[110:111], v103 offset:0x2800
	ds_read_b64_tr_b16 v[112:113], v104 offset:0x2000
	ds_read_b64_tr_b16 v[114:115], v104 offset:0x2800
	ds_read_b64_tr_b16 v[116:117], v104 offset:0x2200
	ds_read_b64_tr_b16 v[118:119], v104 offset:0x2a00
	ds_read_b64_tr_b16 v[120:121], v104 offset:0x2400
	ds_read_b64_tr_b16 v[122:123], v104 offset:0x2c00
	ds_read_b64_tr_b16 v[124:125], v104 offset:0x2600
	ds_read_b64_tr_b16 v[126:127], v104 offset:0x2e00
	s_waitcnt lgkmcnt(0)
; __device__ __forceinline__ int crow(int r, int hi) { return (r & 3) + 8 * (r >> 2) + 4 * hi; }
; __device__ __forceinline__ unsigned f2bf(float f) { unsigned u = __builtin_bit_cast(unsigned, f); return (u + 0x7fffu + ((u >> 16) & 1u)) >> 16; }
; __global__ void __launch_bounds__(NWAVES * 64, 2) mega_fwd(Args args) {
;     ...
;                         B1_STEP(0); B1_STEP(1); B1_STEP(2); B1_STEP(3);
;     ...
;                     }
;                     bf16* dst = KVB + ((size_t)(h * 128 + gc) * 2 + dir) * 32768 + (size_t)(rb * 32) * 256 + half * 128 + r32;
; #pragma unroll
;                     for (int r = 0; r < 16; ++r)
; #pragma unroll
;                         for (int d0 = 0; d0 < 4; ++d0) dst[(size_t)crow(r, hi) * 256 + d0 * 32] = (bf16)f2bf(acc[d0][r]);
	s_nop 0
	v_mfma_f32_32x32x16_bf16 v[16:31], v[108:111], v[112:115], v[16:31]
	v_mfma_f32_32x32x16_bf16 v[48:63], v[108:111], v[116:119], v[48:63]
	v_mfma_f32_32x32x16_bf16 v[32:47], v[108:111], v[120:123], v[32:47]
	v_mfma_f32_32x32x16_bf16 v[0:15], v[108:111], v[124:127], v[0:15]
	ds_read_b64_tr_b16 v[108:109], v103 offset:0x3000
	ds_read_b64_tr_b16 v[110:111], v103 offset:0x3800
	ds_read_b64_tr_b16 v[112:113], v104 offset:0x3000
	ds_read_b64_tr_b16 v[114:115], v104 offset:0x3800
	ds_read_b64_tr_b16 v[116:117], v104 offset:0x3200
	ds_read_b64_tr_b16 v[118:119], v104 offset:0x3a00
	ds_read_b64_tr_b16 v[120:121], v104 offset:0x3400
	ds_read_b64_tr_b16 v[122:123], v104 offset:0x3c00
	ds_read_b64_tr_b16 v[124:125], v104 offset:0x3600
	ds_read_b64_tr_b16 v[126:127], v104 offset:0x3e00
	s_waitcnt lgkmcnt(0)
	s_nop 0
	v_mfma_f32_32x32x16_bf16 v[16:31], v[108:111], v[112:115], v[16:31]
	v_lshl_add_u64 v[112:113], v[98:99], 0, v[66:67]
	v_mfma_f32_32x32x16_bf16 v[48:63], v[108:111], v[116:119], v[48:63]
	s_nop 9
	v_bfe_u32 v107, v16, 16, 1
	v_add3_u32 v16, v16, v107, s33
	global_store_short_d16_hi v[112:113], v16, off
	v_mfma_f32_32x32x16_bf16 v[32:47], v[108:111], v[120:123], v[32:47]
	v_bfe_u32 v16, v48, 16, 1
	v_add3_u32 v16, v48, v16, s33
	global_store_short_d16_hi v[112:113], v16, off offset:64
	v_mfma_f32_32x32x16_bf16 v[0:15], v[108:111], v[124:127], v[0:15]
	s_nop 7
	v_bfe_u32 v16, v32, 16, 1
	v_add3_u32 v16, v32, v16, s33
	global_store_short_d16_hi v[112:113], v16, off offset:128
	s_nop 0
	v_bfe_u32 v16, v0, 16, 1
	v_add3_u32 v0, v0, v16, s33
	global_store_short_d16_hi v[112:113], v0, off offset:192
	v_bfe_u32 v0, v17, 16, 1
	v_add3_u32 v0, v17, v0, s33
	global_store_short_d16_hi v[112:113], v0, off offset:512
	v_bfe_u32 v0, v49, 16, 1
	v_add3_u32 v0, v49, v0, s33
	global_store_short_d16_hi v[112:113], v0, off offset:576
	v_bfe_u32 v0, v33, 16, 1
	v_add3_u32 v0, v33, v0, s33
	global_store_short_d16_hi v[112:113], v0, off offset:640
	v_bfe_u32 v0, v1, 16, 1
	v_add3_u32 v0, v1, v0, s33
	global_store_short_d16_hi v[112:113], v0, off offset:704
	v_bfe_u32 v0, v18, 16, 1
	v_add3_u32 v0, v18, v0, s33
	global_store_short_d16_hi v[112:113], v0, off offset:1024
	v_bfe_u32 v0, v50, 16, 1
	v_add3_u32 v0, v50, v0, s33
	global_store_short_d16_hi v[112:113], v0, off offset:1088
	v_bfe_u32 v0, v34, 16, 1
	v_add3_u32 v0, v34, v0, s33
	global_store_short_d16_hi v[112:113], v0, off offset:1152
	v_bfe_u32 v0, v2, 16, 1
	v_add3_u32 v0, v2, v0, s33
	global_store_short_d16_hi v[112:113], v0, off offset:1216
	v_bfe_u32 v0, v19, 16, 1
	v_add3_u32 v0, v19, v0, s33
	global_store_short_d16_hi v[112:113], v0, off offset:1536
	v_bfe_u32 v0, v51, 16, 1
	v_add3_u32 v0, v51, v0, s33
	global_store_short_d16_hi v[112:113], v0, off offset:1600
	v_bfe_u32 v0, v35, 16, 1
	v_add3_u32 v0, v35, v0, s33
	global_store_short_d16_hi v[112:113], v0, off offset:1664
	v_bfe_u32 v0, v3, 16, 1
	v_add3_u32 v0, v3, v0, s33
	v_bfe_u32 v2, v20, 16, 1
	global_store_short_d16_hi v[112:113], v0, off offset:1728
	v_lshl_add_u64 v[0:1], v[98:99], 0, v[74:75]
	v_add3_u32 v2, v20, v2, s33
	global_store_short_d16_hi v[0:1], v2, off
	v_bfe_u32 v2, v52, 16, 1
	v_add3_u32 v2, v52, v2, s33
	global_store_short_d16_hi v[0:1], v2, off offset:64
	v_bfe_u32 v2, v36, 16, 1
	v_add3_u32 v2, v36, v2, s33
	global_store_short_d16_hi v[0:1], v2, off offset:128
	v_bfe_u32 v2, v4, 16, 1
	v_add3_u32 v2, v4, v2, s33
	global_store_short_d16_hi v[0:1], v2, off offset:192
	v_bfe_u32 v2, v21, 16, 1
	v_lshl_add_u64 v[0:1], v[98:99], 0, v[76:77]
	v_add3_u32 v2, v21, v2, s33
	global_store_short_d16_hi v[0:1], v2, off
	v_bfe_u32 v2, v53, 16, 1
	v_add3_u32 v2, v53, v2, s33
	global_store_short_d16_hi v[0:1], v2, off offset:64
	v_bfe_u32 v2, v37, 16, 1
	v_add3_u32 v2, v37, v2, s33
	global_store_short_d16_hi v[0:1], v2, off offset:128
	v_bfe_u32 v2, v5, 16, 1
	v_add3_u32 v2, v5, v2, s33
	global_store_short_d16_hi v[0:1], v2, off offset:192
	v_bfe_u32 v2, v22, 16, 1
	v_lshl_add_u64 v[0:1], v[98:99], 0, v[78:79]
	v_add3_u32 v2, v22, v2, s33
	global_store_short_d16_hi v[0:1], v2, off
	v_bfe_u32 v2, v54, 16, 1
	v_add3_u32 v2, v54, v2, s33
	global_store_short_d16_hi v[0:1], v2, off offset:64
	v_bfe_u32 v2, v38, 16, 1
	v_add3_u32 v2, v38, v2, s33
	global_store_short_d16_hi v[0:1], v2, off offset:128
	v_bfe_u32 v2, v6, 16, 1
	v_add3_u32 v2, v6, v2, s33
	global_store_short_d16_hi v[0:1], v2, off offset:192
	v_bfe_u32 v2, v23, 16, 1
	v_lshl_add_u64 v[0:1], v[98:99], 0, v[80:81]
	v_add3_u32 v2, v23, v2, s33
	global_store_short_d16_hi v[0:1], v2, off
	v_bfe_u32 v2, v55, 16, 1
	v_add3_u32 v2, v55, v2, s33
	global_store_short_d16_hi v[0:1], v2, off offset:64
	v_bfe_u32 v2, v39, 16, 1
	v_add3_u32 v2, v39, v2, s33
	global_store_short_d16_hi v[0:1], v2, off offset:128
	v_bfe_u32 v2, v7, 16, 1
	v_add3_u32 v2, v7, v2, s33
	global_store_short_d16_hi v[0:1], v2, off offset:192
	v_bfe_u32 v2, v24, 16, 1
	v_lshl_add_u64 v[0:1], v[98:99], 0, v[82:83]
	v_add3_u32 v2, v24, v2, s33
	global_store_short_d16_hi v[0:1], v2, off
	v_bfe_u32 v2, v56, 16, 1
	v_add3_u32 v2, v56, v2, s33
	global_store_short_d16_hi v[0:1], v2, off offset:64
	v_bfe_u32 v2, v40, 16, 1
	v_add3_u32 v2, v40, v2, s33
	global_store_short_d16_hi v[0:1], v2, off offset:128
	v_bfe_u32 v2, v8, 16, 1
	v_add3_u32 v2, v8, v2, s33
	global_store_short_d16_hi v[0:1], v2, off offset:192
	v_bfe_u32 v2, v25, 16, 1
	v_lshl_add_u64 v[0:1], v[98:99], 0, v[84:85]
	v_add3_u32 v2, v25, v2, s33
	global_store_short_d16_hi v[0:1], v2, off
	v_bfe_u32 v2, v57, 16, 1
	v_add3_u32 v2, v57, v2, s33
	global_store_short_d16_hi v[0:1], v2, off offset:64
	v_bfe_u32 v2, v41, 16, 1
	v_add3_u32 v2, v41, v2, s33
; __device__ __forceinline__ int crow(int r, int hi) { return (r & 3) + 8 * (r >> 2) + 4 * hi; }
; __device__ __forceinline__ unsigned f2bf(float f) { unsigned u = __builtin_bit_cast(unsigned, f); return (u + 0x7fffu + ((u >> 16) & 1u)) >> 16; }
; __global__ void __launch_bounds__(NWAVES * 64, 2) mega_fwd(Args args) {
;     ...
;                 for (int dir = 0; dir < 2; ++dir) {
;                     f32x16 acc[4] = {};
; #pragma unroll
;                     for (int tt = 0; tt < 2; ++tt) {
;                         const int ab = abase + dir * 32768 + tt * 16384, bb = bbase + tt * 32768;
;     ...
;                         B1_STEP(0); B1_STEP(1); B1_STEP(2); B1_STEP(3);
;     ...
;                     bf16* dst = KVB + ((size_t)(h * 128 + gc) * 2 + dir) * 32768 + (size_t)(rb * 32) * 256 + half * 128 + r32;
; #pragma unroll
;                     for (int r = 0; r < 16; ++r)
; #pragma unroll
;                         for (int d0 = 0; d0 < 4; ++d0) dst[(size_t)crow(r, hi) * 256 + d0 * 32] = (bf16)f2bf(acc[d0][r]);
	global_store_short_d16_hi v[0:1], v2, off offset:128
	v_bfe_u32 v2, v9, 16, 1
	v_add3_u32 v2, v9, v2, s33
	global_store_short_d16_hi v[0:1], v2, off offset:192
	v_bfe_u32 v2, v26, 16, 1
	v_lshl_add_u64 v[0:1], v[98:99], 0, v[86:87]
	v_add3_u32 v2, v26, v2, s33
	global_store_short_d16_hi v[0:1], v2, off
	v_bfe_u32 v2, v58, 16, 1
	v_add3_u32 v2, v58, v2, s33
	global_store_short_d16_hi v[0:1], v2, off offset:64
	v_bfe_u32 v2, v42, 16, 1
	v_add3_u32 v2, v42, v2, s33
	global_store_short_d16_hi v[0:1], v2, off offset:128
	v_bfe_u32 v2, v10, 16, 1
	v_add3_u32 v2, v10, v2, s33
	global_store_short_d16_hi v[0:1], v2, off offset:192
	v_bfe_u32 v2, v27, 16, 1
	v_lshl_add_u64 v[0:1], v[98:99], 0, v[88:89]
	v_add3_u32 v2, v27, v2, s33
	global_store_short_d16_hi v[0:1], v2, off
	v_bfe_u32 v2, v59, 16, 1
	v_add3_u32 v2, v59, v2, s33
	global_store_short_d16_hi v[0:1], v2, off offset:64
	v_bfe_u32 v2, v43, 16, 1
	v_add3_u32 v2, v43, v2, s33
	global_store_short_d16_hi v[0:1], v2, off offset:128
	v_bfe_u32 v2, v11, 16, 1
	v_add3_u32 v2, v11, v2, s33
	global_store_short_d16_hi v[0:1], v2, off offset:192
	v_bfe_u32 v2, v28, 16, 1
	v_lshl_add_u64 v[0:1], v[98:99], 0, v[90:91]
	v_add3_u32 v2, v28, v2, s33
	global_store_short_d16_hi v[0:1], v2, off
	v_bfe_u32 v2, v60, 16, 1
	v_add3_u32 v2, v60, v2, s33
	global_store_short_d16_hi v[0:1], v2, off offset:64
	v_bfe_u32 v2, v44, 16, 1
	v_add3_u32 v2, v44, v2, s33
	global_store_short_d16_hi v[0:1], v2, off offset:128
	v_bfe_u32 v2, v12, 16, 1
	v_add3_u32 v2, v12, v2, s33
	global_store_short_d16_hi v[0:1], v2, off offset:192
	v_bfe_u32 v2, v29, 16, 1
	v_lshl_add_u64 v[0:1], v[98:99], 0, v[92:93]
	v_add3_u32 v2, v29, v2, s33
	global_store_short_d16_hi v[0:1], v2, off
	v_bfe_u32 v2, v61, 16, 1
	v_add3_u32 v2, v61, v2, s33
	global_store_short_d16_hi v[0:1], v2, off offset:64
	v_bfe_u32 v2, v45, 16, 1
	v_add3_u32 v2, v45, v2, s33
	global_store_short_d16_hi v[0:1], v2, off offset:128
	v_bfe_u32 v2, v13, 16, 1
	v_add3_u32 v2, v13, v2, s33
	global_store_short_d16_hi v[0:1], v2, off offset:192
	v_bfe_u32 v2, v30, 16, 1
	v_lshl_add_u64 v[0:1], v[98:99], 0, v[94:95]
	v_add3_u32 v2, v30, v2, s33
	global_store_short_d16_hi v[0:1], v2, off
	v_bfe_u32 v2, v62, 16, 1
	v_add3_u32 v2, v62, v2, s33
	global_store_short_d16_hi v[0:1], v2, off offset:64
	v_bfe_u32 v2, v46, 16, 1
	v_add3_u32 v2, v46, v2, s33
	global_store_short_d16_hi v[0:1], v2, off offset:128
	v_bfe_u32 v2, v14, 16, 1
	v_add3_u32 v2, v14, v2, s33
	global_store_short_d16_hi v[0:1], v2, off offset:192
	v_bfe_u32 v2, v31, 16, 1
	v_lshl_add_u64 v[0:1], v[98:99], 0, v[96:97]
	v_add3_u32 v2, v31, v2, s33
	global_store_short_d16_hi v[0:1], v2, off
	v_bfe_u32 v2, v63, 16, 1
	v_add3_u32 v2, v63, v2, s33
	global_store_short_d16_hi v[0:1], v2, off offset:64
	v_bfe_u32 v2, v47, 16, 1
	v_add3_u32 v2, v47, v2, s33
	global_store_short_d16_hi v[0:1], v2, off offset:128
	v_bfe_u32 v2, v15, 16, 1
	v_add3_u32 v2, v15, v2, s33
	global_store_short_d16_hi v[0:1], v2, off offset:192
	ds_read_b64_tr_b16 v[0:1], v105 offset:0
	ds_read_b64_tr_b16 v[2:3], v105 offset:0x800
	ds_read_b64_tr_b16 v[4:5], v101 offset:0
	ds_read_b64_tr_b16 v[6:7], v101 offset:0x800
	ds_read_b64_tr_b16 v[8:9], v101 offset:0x200
	ds_read_b64_tr_b16 v[10:11], v101 offset:0xa00
	ds_read_b64_tr_b16 v[12:13], v101 offset:0x400
	ds_read_b64_tr_b16 v[14:15], v101 offset:0xc00
	ds_read_b64_tr_b16 v[108:109], v101 offset:0x600
	ds_read_b64_tr_b16 v[110:111], v101 offset:0xe00
	s_waitcnt lgkmcnt(0)
	s_nop 0
	v_mfma_f32_32x32x16_bf16 v[16:31], v[0:3], v[4:7], 0
	v_mfma_f32_32x32x16_bf16 v[48:63], v[0:3], v[8:11], 0
	v_mfma_f32_32x32x16_bf16 v[32:47], v[0:3], v[12:15], 0
	v_mfma_f32_32x32x16_bf16 v[0:15], v[0:3], v[108:111], 0
	ds_read_b64_tr_b16 v[108:109], v105 offset:0x1000
	ds_read_b64_tr_b16 v[110:111], v105 offset:0x1800
	ds_read_b64_tr_b16 v[112:113], v101 offset:0x1000
	ds_read_b64_tr_b16 v[114:115], v101 offset:0x1800
	ds_read_b64_tr_b16 v[116:117], v101 offset:0x1200
	ds_read_b64_tr_b16 v[118:119], v101 offset:0x1a00
	ds_read_b64_tr_b16 v[120:121], v101 offset:0x1400
	ds_read_b64_tr_b16 v[122:123], v101 offset:0x1c00
	ds_read_b64_tr_b16 v[124:125], v101 offset:0x1600
	ds_read_b64_tr_b16 v[126:127], v101 offset:0x1e00
	s_waitcnt lgkmcnt(0)
	s_nop 0
	v_mfma_f32_32x32x16_bf16 v[16:31], v[108:111], v[112:115], v[16:31]
	v_mfma_f32_32x32x16_bf16 v[48:63], v[108:111], v[116:119], v[48:63]
	v_mfma_f32_32x32x16_bf16 v[32:47], v[108:111], v[120:123], v[32:47]
	v_mfma_f32_32x32x16_bf16 v[0:15], v[108:111], v[124:127], v[0:15]
	ds_read_b64_tr_b16 v[108:109], v105 offset:0x2000
	ds_read_b64_tr_b16 v[110:111], v105 offset:0x2800
	ds_read_b64_tr_b16 v[112:113], v101 offset:0x2000
	ds_read_b64_tr_b16 v[114:115], v101 offset:0x2800
	ds_read_b64_tr_b16 v[116:117], v101 offset:0x2200
	ds_read_b64_tr_b16 v[118:119], v101 offset:0x2a00
	ds_read_b64_tr_b16 v[120:121], v101 offset:0x2400
	ds_read_b64_tr_b16 v[122:123], v101 offset:0x2c00
	ds_read_b64_tr_b16 v[124:125], v101 offset:0x2600
	ds_read_b64_tr_b16 v[126:127], v101 offset:0x2e00
	s_waitcnt lgkmcnt(0)
	s_nop 0
	v_mfma_f32_32x32x16_bf16 v[16:31], v[108:111], v[112:115], v[16:31]
	v_mfma_f32_32x32x16_bf16 v[48:63], v[108:111], v[116:119], v[48:63]
	v_mfma_f32_32x32x16_bf16 v[32:47], v[108:111], v[120:123], v[32:47]
	v_mfma_f32_32x32x16_bf16 v[0:15], v[108:111], v[124:127], v[0:15]
	ds_read_b64_tr_b16 v[108:109], v105 offset:0x3000
	ds_read_b64_tr_b16 v[110:111], v105 offset:0x3800
	ds_read_b64_tr_b16 v[112:113], v101 offset:0x3000
	ds_read_b64_tr_b16 v[114:115], v101 offset:0x3800
	ds_read_b64_tr_b16 v[116:117], v101 offset:0x3200
	ds_read_b64_tr_b16 v[118:119], v101 offset:0x3a00
	ds_read_b64_tr_b16 v[120:121], v101 offset:0x3400
	ds_read_b64_tr_b16 v[122:123], v101 offset:0x3c00
	ds_read_b64_tr_b16 v[124:125], v101 offset:0x3600
	ds_read_b64_tr_b16 v[126:127], v101 offset:0x3e00
	s_waitcnt lgkmcnt(0)
; __device__ __forceinline__ int crow(int r, int hi) { return (r & 3) + 8 * (r >> 2) + 4 * hi; }
; __device__ __forceinline__ unsigned f2bf(float f) { unsigned u = __builtin_bit_cast(unsigned, f); return (u + 0x7fffu + ((u >> 16) & 1u)) >> 16; }
; __global__ void __launch_bounds__(NWAVES * 64, 2) mega_fwd(Args args) {
;     ...
;                         const int ab = abase + dir * 32768 + tt * 16384, bb = bbase + tt * 32768;
;     ...
;                         B1_STEP(0); B1_STEP(1); B1_STEP(2); B1_STEP(3);
;     ...
;                     }
;                     bf16* dst = KVB + ((size_t)(h * 128 + gc) * 2 + dir) * 32768 + (size_t)(rb * 32) * 256 + half * 128 + r32;
; #pragma unroll
;                     for (int r = 0; r < 16; ++r)
; #pragma unroll
;                         for (int d0 = 0; d0 < 4; ++d0) dst[(size_t)crow(r, hi) * 256 + d0 * 32] = (bf16)f2bf(acc[d0][r]);
	s_nop 0
	v_mfma_f32_32x32x16_bf16 v[16:31], v[108:111], v[112:115], v[16:31]
	v_mfma_f32_32x32x16_bf16 v[48:63], v[108:111], v[116:119], v[48:63]
	v_mfma_f32_32x32x16_bf16 v[32:47], v[108:111], v[120:123], v[32:47]
	v_mfma_f32_32x32x16_bf16 v[0:15], v[108:111], v[124:127], v[0:15]
	ds_read_b64_tr_b16 v[108:109], v106 offset:0
	ds_read_b64_tr_b16 v[110:111], v106 offset:0x800
	ds_read_b64_tr_b16 v[112:113], v104 offset:0
	ds_read_b64_tr_b16 v[114:115], v104 offset:0x800
	ds_read_b64_tr_b16 v[116:117], v104 offset:0x200
	ds_read_b64_tr_b16 v[118:119], v104 offset:0xa00
	ds_read_b64_tr_b16 v[120:121], v104 offset:0x400
	ds_read_b64_tr_b16 v[122:123], v104 offset:0xc00
	ds_read_b64_tr_b16 v[124:125], v104 offset:0x600
	ds_read_b64_tr_b16 v[126:127], v104 offset:0xe00
	s_waitcnt lgkmcnt(0)
	s_nop 0
	v_mfma_f32_32x32x16_bf16 v[16:31], v[108:111], v[112:115], v[16:31]
	v_mfma_f32_32x32x16_bf16 v[48:63], v[108:111], v[116:119], v[48:63]
	v_mfma_f32_32x32x16_bf16 v[32:47], v[108:111], v[120:123], v[32:47]
	v_mfma_f32_32x32x16_bf16 v[0:15], v[108:111], v[124:127], v[0:15]
	ds_read_b64_tr_b16 v[108:109], v106 offset:0x1000
	ds_read_b64_tr_b16 v[110:111], v106 offset:0x1800
	ds_read_b64_tr_b16 v[112:113], v104 offset:0x1000
	ds_read_b64_tr_b16 v[114:115], v104 offset:0x1800
	ds_read_b64_tr_b16 v[116:117], v104 offset:0x1200
	ds_read_b64_tr_b16 v[118:119], v104 offset:0x1a00
	ds_read_b64_tr_b16 v[120:121], v104 offset:0x1400
	ds_read_b64_tr_b16 v[122:123], v104 offset:0x1c00
	ds_read_b64_tr_b16 v[124:125], v104 offset:0x1600
	ds_read_b64_tr_b16 v[126:127], v104 offset:0x1e00
	s_waitcnt lgkmcnt(0)
	s_nop 0
	v_mfma_f32_32x32x16_bf16 v[16:31], v[108:111], v[112:115], v[16:31]
	v_mfma_f32_32x32x16_bf16 v[48:63], v[108:111], v[116:119], v[48:63]
	v_mfma_f32_32x32x16_bf16 v[32:47], v[108:111], v[120:123], v[32:47]
	v_mfma_f32_32x32x16_bf16 v[0:15], v[108:111], v[124:127], v[0:15]
	ds_read_b64_tr_b16 v[108:109], v106 offset:0x2000
	ds_read_b64_tr_b16 v[110:111], v106 offset:0x2800
	ds_read_b64_tr_b16 v[112:113], v104 offset:0x2000
	ds_read_b64_tr_b16 v[114:115], v104 offset:0x2800
	ds_read_b64_tr_b16 v[116:117], v104 offset:0x2200
	ds_read_b64_tr_b16 v[118:119], v104 offset:0x2a00
	ds_read_b64_tr_b16 v[120:121], v104 offset:0x2400
	ds_read_b64_tr_b16 v[122:123], v104 offset:0x2c00
	ds_read_b64_tr_b16 v[124:125], v104 offset:0x2600
	ds_read_b64_tr_b16 v[126:127], v104 offset:0x2e00
	s_waitcnt lgkmcnt(0)
	s_nop 0
	v_mfma_f32_32x32x16_bf16 v[16:31], v[108:111], v[112:115], v[16:31]
	v_mfma_f32_32x32x16_bf16 v[48:63], v[108:111], v[116:119], v[48:63]
	v_mfma_f32_32x32x16_bf16 v[32:47], v[108:111], v[120:123], v[32:47]
	v_mfma_f32_32x32x16_bf16 v[0:15], v[108:111], v[124:127], v[0:15]
	ds_read_b64_tr_b16 v[108:109], v106 offset:0x3000
	ds_read_b64_tr_b16 v[110:111], v106 offset:0x3800
	ds_read_b64_tr_b16 v[112:113], v104 offset:0x3000
	ds_read_b64_tr_b16 v[114:115], v104 offset:0x3800
	ds_read_b64_tr_b16 v[116:117], v104 offset:0x3200
	ds_read_b64_tr_b16 v[118:119], v104 offset:0x3a00
	ds_read_b64_tr_b16 v[120:121], v104 offset:0x3400
	ds_read_b64_tr_b16 v[122:123], v104 offset:0x3c00
	ds_read_b64_tr_b16 v[124:125], v104 offset:0x3600
	ds_read_b64_tr_b16 v[126:127], v104 offset:0x3e00
	s_waitcnt lgkmcnt(0)
	s_nop 0
	v_mfma_f32_32x32x16_bf16 v[16:31], v[108:111], v[112:115], v[16:31]
	v_lshl_add_u64 v[98:99], v[98:99], 0, s[12:13]
	v_lshl_add_u64 v[112:113], v[98:99], 0, v[66:67]
	s_add_i32 s0, s0, s48
	s_cmpk_gt_i32 s0, 0x3ff
	v_mfma_f32_32x32x16_bf16 v[48:63], v[108:111], v[116:119], v[48:63]
	s_nop 6
	v_bfe_u32 v107, v16, 16, 1
	v_add3_u32 v16, v16, v107, s33
	global_store_short_d16_hi v[112:113], v16, off
	v_mfma_f32_32x32x16_bf16 v[32:47], v[108:111], v[120:123], v[32:47]
	s_nop 0
	v_bfe_u32 v16, v48, 16, 1
	v_add3_u32 v16, v48, v16, s33
	global_store_short_d16_hi v[112:113], v16, off offset:64
	v_mfma_f32_32x32x16_bf16 v[0:15], v[108:111], v[124:127], v[0:15]
	s_nop 6
	v_bfe_u32 v16, v32, 16, 1
	v_add3_u32 v16, v32, v16, s33
	global_store_short_d16_hi v[112:113], v16, off offset:128
	v_lshl_add_u64 v[108:109], v[98:99], 0, v[68:69]
	s_nop 0
	v_bfe_u32 v16, v0, 16, 1
	v_add3_u32 v0, v0, v16, s33
	global_store_short_d16_hi v[112:113], v0, off offset:192
	v_bfe_u32 v0, v17, 16, 1
	v_add3_u32 v0, v17, v0, s33
	global_store_short_d16_hi v[108:109], v0, off
	v_bfe_u32 v0, v49, 16, 1
	v_add3_u32 v0, v49, v0, s33
	global_store_short_d16_hi v[108:109], v0, off offset:64
	v_bfe_u32 v0, v33, 16, 1
	v_add3_u32 v0, v33, v0, s33
	global_store_short_d16_hi v[108:109], v0, off offset:128
	v_bfe_u32 v0, v1, 16, 1
	v_add3_u32 v0, v1, v0, s33
	v_bfe_u32 v16, v18, 16, 1
	global_store_short_d16_hi v[108:109], v0, off offset:192
	v_lshl_add_u64 v[0:1], v[98:99], 0, v[70:71]
	v_add3_u32 v16, v18, v16, s33
	global_store_short_d16_hi v[0:1], v16, off
	v_bfe_u32 v16, v50, 16, 1
	v_add3_u32 v16, v50, v16, s33
	global_store_short_d16_hi v[0:1], v16, off offset:64
	v_bfe_u32 v16, v34, 16, 1
	v_add3_u32 v16, v34, v16, s33
	global_store_short_d16_hi v[0:1], v16, off offset:128
	v_bfe_u32 v16, v2, 16, 1
	v_add3_u32 v2, v2, v16, s33
	global_store_short_d16_hi v[0:1], v2, off offset:192
	v_bfe_u32 v2, v19, 16, 1
	v_lshl_add_u64 v[0:1], v[98:99], 0, v[72:73]
	v_add3_u32 v2, v19, v2, s33
	global_store_short_d16_hi v[0:1], v2, off
	v_bfe_u32 v2, v51, 16, 1
	v_add3_u32 v2, v51, v2, s33
	global_store_short_d16_hi v[0:1], v2, off offset:64
	v_bfe_u32 v2, v35, 16, 1
	v_add3_u32 v2, v35, v2, s33
	global_store_short_d16_hi v[0:1], v2, off offset:128
	v_bfe_u32 v2, v3, 16, 1
	v_add3_u32 v2, v3, v2, s33
	global_store_short_d16_hi v[0:1], v2, off offset:192
	v_bfe_u32 v2, v20, 16, 1
; __device__ __forceinline__ int crow(int r, int hi) { return (r & 3) + 8 * (r >> 2) + 4 * hi; }
; __device__ __forceinline__ unsigned f2bf(float f) { unsigned u = __builtin_bit_cast(unsigned, f); return (u + 0x7fffu + ((u >> 16) & 1u)) >> 16; }
; __global__ void __launch_bounds__(NWAVES * 64, 2) mega_fwd(Args args) {
;     ...
;                     bf16* dst = KVB + ((size_t)(h * 128 + gc) * 2 + dir) * 32768 + (size_t)(rb * 32) * 256 + half * 128 + r32;
; #pragma unroll
;                     for (int r = 0; r < 16; ++r)
; #pragma unroll
;                         for (int d0 = 0; d0 < 4; ++d0) dst[(size_t)crow(r, hi) * 256 + d0 * 32] = (bf16)f2bf(acc[d0][r]);
;                 }
;                 __syncthreads();
;             }
	v_lshl_add_u64 v[0:1], v[98:99], 0, v[74:75]
	v_add3_u32 v2, v20, v2, s33
	global_store_short_d16_hi v[0:1], v2, off
	v_bfe_u32 v2, v52, 16, 1
	v_add3_u32 v2, v52, v2, s33
	global_store_short_d16_hi v[0:1], v2, off offset:64
	v_bfe_u32 v2, v36, 16, 1
	v_add3_u32 v2, v36, v2, s33
	global_store_short_d16_hi v[0:1], v2, off offset:128
	v_bfe_u32 v2, v4, 16, 1
	v_add3_u32 v2, v4, v2, s33
	global_store_short_d16_hi v[0:1], v2, off offset:192
	v_bfe_u32 v2, v21, 16, 1
	v_lshl_add_u64 v[0:1], v[98:99], 0, v[76:77]
	v_add3_u32 v2, v21, v2, s33
	global_store_short_d16_hi v[0:1], v2, off
	v_bfe_u32 v2, v53, 16, 1
	v_add3_u32 v2, v53, v2, s33
	global_store_short_d16_hi v[0:1], v2, off offset:64
	v_bfe_u32 v2, v37, 16, 1
	v_add3_u32 v2, v37, v2, s33
	global_store_short_d16_hi v[0:1], v2, off offset:128
	v_bfe_u32 v2, v5, 16, 1
	v_add3_u32 v2, v5, v2, s33
	global_store_short_d16_hi v[0:1], v2, off offset:192
	v_bfe_u32 v2, v22, 16, 1
	v_lshl_add_u64 v[0:1], v[98:99], 0, v[78:79]
	v_add3_u32 v2, v22, v2, s33
	global_store_short_d16_hi v[0:1], v2, off
	v_bfe_u32 v2, v54, 16, 1
	v_add3_u32 v2, v54, v2, s33
	global_store_short_d16_hi v[0:1], v2, off offset:64
	v_bfe_u32 v2, v38, 16, 1
	v_add3_u32 v2, v38, v2, s33
	global_store_short_d16_hi v[0:1], v2, off offset:128
	v_bfe_u32 v2, v6, 16, 1
	v_add3_u32 v2, v6, v2, s33
	global_store_short_d16_hi v[0:1], v2, off offset:192
	v_bfe_u32 v2, v23, 16, 1
	v_lshl_add_u64 v[0:1], v[98:99], 0, v[80:81]
	v_add3_u32 v2, v23, v2, s33
	global_store_short_d16_hi v[0:1], v2, off
	v_bfe_u32 v2, v55, 16, 1
	v_add3_u32 v2, v55, v2, s33
	global_store_short_d16_hi v[0:1], v2, off offset:64
	v_bfe_u32 v2, v39, 16, 1
	v_add3_u32 v2, v39, v2, s33
	global_store_short_d16_hi v[0:1], v2, off offset:128
	v_bfe_u32 v2, v7, 16, 1
	v_add3_u32 v2, v7, v2, s33
	global_store_short_d16_hi v[0:1], v2, off offset:192
	v_bfe_u32 v2, v24, 16, 1
	v_lshl_add_u64 v[0:1], v[98:99], 0, v[82:83]
	v_add3_u32 v2, v24, v2, s33
	global_store_short_d16_hi v[0:1], v2, off
	v_bfe_u32 v2, v56, 16, 1
	v_add3_u32 v2, v56, v2, s33
	global_store_short_d16_hi v[0:1], v2, off offset:64
	v_bfe_u32 v2, v40, 16, 1
	v_add3_u32 v2, v40, v2, s33
	global_store_short_d16_hi v[0:1], v2, off offset:128
	v_bfe_u32 v2, v8, 16, 1
	v_add3_u32 v2, v8, v2, s33
	global_store_short_d16_hi v[0:1], v2, off offset:192
	v_bfe_u32 v2, v25, 16, 1
	v_lshl_add_u64 v[0:1], v[98:99], 0, v[84:85]
	v_add3_u32 v2, v25, v2, s33
	global_store_short_d16_hi v[0:1], v2, off
	v_bfe_u32 v2, v57, 16, 1
	v_add3_u32 v2, v57, v2, s33
	global_store_short_d16_hi v[0:1], v2, off offset:64
	v_bfe_u32 v2, v41, 16, 1
	v_add3_u32 v2, v41, v2, s33
	global_store_short_d16_hi v[0:1], v2, off offset:128
	v_bfe_u32 v2, v9, 16, 1
	v_add3_u32 v2, v9, v2, s33
	global_store_short_d16_hi v[0:1], v2, off offset:192
	v_bfe_u32 v2, v26, 16, 1
	v_lshl_add_u64 v[0:1], v[98:99], 0, v[86:87]
	v_add3_u32 v2, v26, v2, s33
	global_store_short_d16_hi v[0:1], v2, off
	v_bfe_u32 v2, v58, 16, 1
	v_add3_u32 v2, v58, v2, s33
	global_store_short_d16_hi v[0:1], v2, off offset:64
	v_bfe_u32 v2, v42, 16, 1
	v_add3_u32 v2, v42, v2, s33
	global_store_short_d16_hi v[0:1], v2, off offset:128
	v_bfe_u32 v2, v10, 16, 1
	v_add3_u32 v2, v10, v2, s33
	global_store_short_d16_hi v[0:1], v2, off offset:192
	v_bfe_u32 v2, v27, 16, 1
	v_lshl_add_u64 v[0:1], v[98:99], 0, v[88:89]
	v_add3_u32 v2, v27, v2, s33
	global_store_short_d16_hi v[0:1], v2, off
	v_bfe_u32 v2, v59, 16, 1
	v_add3_u32 v2, v59, v2, s33
	global_store_short_d16_hi v[0:1], v2, off offset:64
	v_bfe_u32 v2, v43, 16, 1
	v_add3_u32 v2, v43, v2, s33
	global_store_short_d16_hi v[0:1], v2, off offset:128
	v_bfe_u32 v2, v11, 16, 1
	v_add3_u32 v2, v11, v2, s33
	global_store_short_d16_hi v[0:1], v2, off offset:192
	v_bfe_u32 v2, v28, 16, 1
	v_lshl_add_u64 v[0:1], v[98:99], 0, v[90:91]
	v_add3_u32 v2, v28, v2, s33
	global_store_short_d16_hi v[0:1], v2, off
	v_bfe_u32 v2, v60, 16, 1
	v_add3_u32 v2, v60, v2, s33
	global_store_short_d16_hi v[0:1], v2, off offset:64
	v_bfe_u32 v2, v44, 16, 1
	v_add3_u32 v2, v44, v2, s33
	global_store_short_d16_hi v[0:1], v2, off offset:128
	v_bfe_u32 v2, v12, 16, 1
	v_add3_u32 v2, v12, v2, s33
	global_store_short_d16_hi v[0:1], v2, off offset:192
	v_bfe_u32 v2, v29, 16, 1
	v_lshl_add_u64 v[0:1], v[98:99], 0, v[92:93]
	v_add3_u32 v2, v29, v2, s33
	global_store_short_d16_hi v[0:1], v2, off
	v_bfe_u32 v2, v61, 16, 1
	v_add3_u32 v2, v61, v2, s33
	global_store_short_d16_hi v[0:1], v2, off offset:64
	v_bfe_u32 v2, v45, 16, 1
	v_add3_u32 v2, v45, v2, s33
	global_store_short_d16_hi v[0:1], v2, off offset:128
	v_bfe_u32 v2, v13, 16, 1
	v_add3_u32 v2, v13, v2, s33
	global_store_short_d16_hi v[0:1], v2, off offset:192
	v_bfe_u32 v2, v30, 16, 1
	v_lshl_add_u64 v[0:1], v[98:99], 0, v[94:95]
	v_add3_u32 v2, v30, v2, s33
	global_store_short_d16_hi v[0:1], v2, off
	v_bfe_u32 v2, v62, 16, 1
	v_add3_u32 v2, v62, v2, s33
	global_store_short_d16_hi v[0:1], v2, off offset:64
	v_bfe_u32 v2, v46, 16, 1
	v_add3_u32 v2, v46, v2, s33
	global_store_short_d16_hi v[0:1], v2, off offset:128
	v_bfe_u32 v2, v14, 16, 1
	v_add3_u32 v2, v14, v2, s33
	global_store_short_d16_hi v[0:1], v2, off offset:192
	v_bfe_u32 v2, v31, 16, 1
	v_lshl_add_u64 v[0:1], v[98:99], 0, v[96:97]
	v_add3_u32 v2, v31, v2, s33
	global_store_short_d16_hi v[0:1], v2, off
	v_bfe_u32 v2, v63, 16, 1
	v_add3_u32 v2, v63, v2, s33
	global_store_short_d16_hi v[0:1], v2, off offset:64
	v_bfe_u32 v2, v47, 16, 1
	v_add3_u32 v2, v47, v2, s33
	global_store_short_d16_hi v[0:1], v2, off offset:128
	v_bfe_u32 v2, v15, 16, 1
	v_add3_u32 v2, v15, v2, s33
	global_store_short_d16_hi v[0:1], v2, off offset:192
	s_waitcnt vmcnt(63) expcnt(7) lgkmcnt(15)
	s_barrier
	s_cbranch_scc0 .LBB0_256
